# v015 + G4: x1 tile preloaded into accumulators (phase 1 without loads), prologue full vmcnt(0) drain removed (template waits suffice)
# speedup vs baseline: 1.0119x; 1.0119x over previous
; #define PG8_STAGE(bufoff, gbase, voff) do { _Pragma("unroll") for (int _i = 0; _i < 2; ++_i) \
;         __builtin_amdgcn_global_load_lds((const unsigned*)((const char*)(gbase) + (voff)[_i]), (LAS unsigned*)(lds + (bufoff) + ldsw + _i * 8192), 16, 0, 0); } while (0)
; #define PG8_WAIT_V(n) asm volatile("s_waitcnt vmcnt(" #n ")" ::: "memory")
; #define PG8_BAR __builtin_amdgcn_s_barrier()
; template <class Epi, class Sched, bool ALIGN_EPI = true>
; __device__ __forceinline__ void gemm_phase(LAS unsigned char* lds, const Gemm g, const Sched& S, const Epi& E) {
;     ...
;     const char* cA = (const char*)g.A + (size_t)cur.pm * tstep; const char* cB = (const char*)g.Bt + (size_t)cur.pn * tstep;
;     S.a_ready(cur);
;     PG8_STAGE(PG8_SB(0, 0), cB, voffB); PG8_STAGE(PG8_SB(0, 1), cB + hstep, voffB); PG8_STAGE(PG8_SA(0, 0), cA, voffA); PG8_STAGE(PG8_SA(0, 1), cA + hstep, voffA);
;     if (wr == 1) PG8_BAR;
;     PG8_WAIT_V(2); PG8_BAR;
;     PG8_STAGE(PG8_SB(1, 0), cB + kstep, voffB); PG8_STAGE(PG8_SA(1, 0), cA + kstep, voffA); PG8_STAGE(PG8_SB(1, 1), cB + hstep + kstep, voffB);
;     PG8_WAIT_V(6); PG8_BAR;
.LBB0_846:
	v_bfe_u32 v10, v8, 4, 2
	s_add_u32 s51, s86, 0xe000
	v_and_b32_e32 v9, 15, v8
	v_lshlrev_b32_e32 v11, 4, v10
	v_lshlrev_b32_e32 v8, 2, v8
	s_mov_b64 s[20:21], 0x80
	s_addc_u32 s52, s87, 0
	s_and_b32 s53, s2, 3
	v_lshl_or_b32 v180, s3, 6, v9
	v_lshl_or_b32 v9, v9, 6, v11
	s_lshl_b32 s2, s3, 13
	v_and_b32_e32 v8, 32, v8
	s_add_i32 m0, s45, 0x18000
	v_lshl_add_u64 v[6:7], v[6:7], 0, s[20:21]
	v_bitop3_b32 v11, v9, s2, v8 bitop3:0xde
	s_lshl_b32 s2, s53, 12
	s_waitcnt vmcnt(2)
	s_barrier
	global_load_lds_dwordx4 v[6:7], off
	v_lshl_add_u64 v[4:5], v[4:5], 0, s[20:21]
	s_add_i32 m0, s45, 0x1a000
	s_add_i32 s54, s45, 0x8000
	s_add_i32 s55, s45, 0xa000
	v_bitop3_b32 v181, v9, s2, v8 bitop3:0xde
	global_load_lds_dwordx4 v[4:5], off
	v_lshl_add_u64 v[0:1], v[0:1], 0, s[20:21]
	s_mov_b32 m0, s54
	s_add_u32 s2, s14, 0x80080
	global_load_lds_dwordx4 v[0:1], off
	v_lshl_add_u64 v[0:1], v[2:3], 0, s[20:21]
	s_mov_b32 m0, s55
	s_addc_u32 s3, s15, 0
	global_load_lds_dwordx4 v[0:1], off
	s_add_i32 m0, s45, 0x1c000
	v_lshl_add_u64 v[0:1], s[2:3], 0, v[144:145]
	global_load_lds_dwordx4 v[0:1], off
	v_lshl_add_u64 v[0:1], s[2:3], 0, v[146:147]
	s_add_i32 m0, s45, 0x1e000
	s_cmpk_lt_u32 s16, 0x100
	global_load_lds_dwordx4 v[0:1], off
	s_cselect_b64 s[22:23], -1, 0
	s_lshr_b32 s2, s94, 3
	s_lshl_b32 s3, s94, 5
	s_and_b32 s2, s2, 24
	s_and_b32 s3, s3, 32
	s_or_b32 s2, s3, s2
	s_lshr_b32 s57, s2, 3
	s_ashr_i32 s2, s94, 31
	s_lshl_b32 s16, s94, 2
	s_lshr_b32 s2, s2, 29
	s_and_b32 s16, s16, 24
	s_bfe_u32 s3, s94, 0x30003
	s_add_i32 s2, s94, s2
	s_or_b32 s56, s16, s3
	s_ashr_i32 s3, s2, 3
	s_and_b32 s2, s2, -8
	s_sub_i32 s2, s94, s2
	s_lshl_b32 s16, s2, 5
	s_cmp_lt_i32 s2, 0
	s_mul_i32 s2, s2, 33
	s_cselect_b32 s2, s2, s16
	s_add_i32 s2, s2, s3
	s_ashr_i32 s3, s2, 31
	s_lshr_b32 s3, s3, 26
	s_add_i32 s3, s2, s3
	s_ashr_i32 s16, s3, 6
	s_andn2_b32 s3, s3, 63
	s_sub_i32 s2, s2, s3
	s_bfe_i32 s3, s2, 0x80000
	s_bfe_u32 s3, s3, 0x3000c
	s_add_i32 s3, s2, s3
	s_lshl_b32 s33, s16, 3
	s_bfe_i32 s16, s3, 0x80000
	s_and_b32 s3, s3, 0xf8
	s_waitcnt vmcnt(6)
	v_lshlrev_b32_e32 v0, 2, v10
	s_sub_i32 s2, s2, s3
	v_lshl_or_b32 v182, s53, 5, v0
	v_lshlrev_b32_e32 v0, 5, v10
	v_mov_b32_e32 v1, v145
	s_sext_i32_i16 s16, s16
	s_sext_i32_i8 s2, s2
	v_readlane_b32 s80, v234, 22
	v_readlane_b32 s82, v234, 31
	v_cmp_eq_u32_e64 s[4:5], 0, v10
	v_lshl_add_u64 v[148:149], s[0:1], 0, v[0:1]
	s_add_i32 s33, s33, s2
	s_ashr_i32 s58, s16, 3
	s_add_i32 s59, 0, 0x10000
	s_add_i32 s60, 0, 0x14000
	v_add_u32_e32 v183, 0, v11
	v_mov_b32_e32 v184, 0x358637bd
	s_mov_b32 s61, 0
	v_mov_b32_e32 v8, v208
	v_mov_b32_e32 v9, v209
	v_mov_b32_e32 v10, v210
	v_mov_b32_e32 v11, v211
	v_mov_b32_e32 v4, v212
	v_mov_b32_e32 v5, v213
	v_mov_b32_e32 v6, v214
	v_mov_b32_e32 v7, v215
	v_mov_b32_e32 v0, v216
	v_mov_b32_e32 v1, v217
	v_mov_b32_e32 v2, v218
	v_mov_b32_e32 v3, v219
	v_readlane_b32 s81, v234, 23
	v_readlane_b32 s83, v234, 32
	s_barrier
	s_branch .LBB0_849
